# v25 + same staged-tile LDS read pipelining applied to the second gated attention-output epilogue ladder
# baseline (speedup 1.0000x reference)
; #define LAS __attribute__((address_space(3)))
; __device__ __forceinline__ int crow(int r, int hi) { return (r & 3) + 8 * (r >> 2) + 4 * hi; }
; __device__ __forceinline__ void row_recip(float l_reg, float (&rli)[16], LAS float* li, int r32, int hi) {
;     { auto rr = __builtin_amdgcn_permlane32_swap(__float_as_uint(l_reg), __float_as_uint(l_reg), false, false);
;       l_reg = __uint_as_float(rr[0]) + __uint_as_float(rr[1]); }
;     if (hi == 0) li[r32] = l_reg;
;     asm volatile("s_waitcnt lgkmcnt(0)" ::: "memory");
; #pragma unroll
;     for (int r = 0; r < 16; ++r) rli[r] = __builtin_amdgcn_rcpf(li[crow(r, hi)]);
;     asm volatile("s_waitcnt lgkmcnt(0)" ::: "memory");
; }
; template <bool SUBLN>
; __device__ __forceinline__ void attn_out(const AttnBufs& T, f32x16 (&o)[4], int type, int h, size_t orow0, LAS char* lds, int wid, int lane, int r32, int hi) {
;     const int rr = lane >> 5, c4 = (lane & 31) * 4;
;     const int col = type * 1024 + h * 128 + c4;
;     const bf16_t* gp = T.GATE + (orow0 + rr) * 3072 + col; bf16_t* op = T.BR + (orow0 + rr) * 3072 + col;
;     u32x2 gg[16];
; #pragma unroll
;     for (int i = 0; i < 16; ++i) gg[i] = *(const u32x2*)(gp + (size_t)i * 2 * 3072);
;     __syncthreads();
; __device__ __forceinline__ void attn_item(const AttnBufs& T, int type, int b, int h, int qrow0, int NT, LAS char* lds, int tid_) {
;     ...
;         for (int d0 = 0; d0 < 4; ++d0)
; #pragma unroll
;             for (int r = 0; r < 16; ++r) o[d0][r] *= rli[r];
.LBB0_107:
	s_or_b64 exec, exec, s[44:45]
	s_waitcnt lgkmcnt(0)
	v_add_u32_e32 v8, s90, v144
	ds_read_b128 v[0:3], v8
	ds_read_b128 v[4:7], v8 offset:32
	v_readlane_b32 s2, v251, 46
	v_readlane_b32 s3, v251, 47
	s_movk_i32 s5, 0x1800
	s_waitcnt lgkmcnt(0)
	v_rcp_f32_e32 v9, v0
	v_rcp_f32_e32 v10, v1
	v_rcp_f32_e32 v11, v2
	v_rcp_f32_e32 v12, v3
	ds_read_b128 v[0:3], v8 offset:64
	v_rcp_f32_e32 v13, v4
	v_rcp_f32_e32 v14, v5
	v_rcp_f32_e32 v15, v6
	v_rcp_f32_e32 v80, v7
	ds_read_b128 v[4:7], v8 offset:96
	s_waitcnt lgkmcnt(0)
	v_rcp_f32_e32 v0, v0
	v_rcp_f32_e32 v1, v1
	v_rcp_f32_e32 v2, v2
	v_rcp_f32_e32 v3, v3
	v_mul_f32_e32 v87, v24, v0
	v_mul_f32_e32 v40, v40, v0
	v_mul_f32_e32 v56, v56, v0
	v_mul_f32_e32 v72, v72, v0
	v_lshlrev_b32_e32 v0, 2, v182
	v_mul_f32_e32 v23, v23, v80
	v_mul_f32_e32 v102, v39, v80
	v_mul_f32_e32 v55, v55, v80
	v_mul_f32_e32 v71, v71, v80
	v_and_b32_e32 v80, 0x7c, v0
	v_rcp_f32_e32 v4, v4
	v_mul_f32_e32 v88, v25, v1
	v_mul_f32_e32 v89, v26, v2
	v_mul_f32_e32 v90, v27, v3
	v_mul_f32_e32 v42, v42, v2
	v_mul_f32_e32 v43, v43, v3
	v_mul_f32_e32 v58, v58, v2
	v_mul_f32_e32 v59, v59, v3
	v_mul_f32_e32 v74, v74, v2
	v_mul_f32_e32 v75, v75, v3
	v_or_b32_e32 v0, s48, v80
	v_lshl_add_u64 v[24:25], s[36:37], 0, v[176:177]
	v_mov_b64_e32 v[2:3], s[2:3]
	v_rcp_f32_e32 v5, v5
	v_mul_f32_e32 v41, v41, v1
	v_mul_f32_e32 v57, v57, v1
	v_mul_f32_e32 v73, v73, v1
	v_mad_u64_u32 v[2:3], s[2:3], v24, s5, v[2:3]
	v_ashrrev_i32_e32 v1, 31, v0
	v_rcp_f32_e32 v6, v6
	v_mad_i32_i24 v3, v25, s5, v3
	v_lshlrev_b64 v[0:1], 1, v[0:1]
	v_rcp_f32_e32 v7, v7
	v_lshl_add_u64 v[2:3], v[2:3], 0, v[0:1]
	v_mul_f32_e32 v91, v28, v4
	v_mul_f32_e32 v44, v44, v4
	v_mul_f32_e32 v60, v60, v4
	v_mul_f32_e32 v76, v76, v4
	v_add_co_u32_e32 v4, vcc, s40, v2
	v_mul_f32_e32 v92, v29, v5
	v_mul_f32_e32 v45, v45, v5
	v_mul_f32_e32 v61, v61, v5
	v_mul_f32_e32 v77, v77, v5
	v_addc_co_u32_e32 v5, vcc, 0, v3, vcc
	v_mul_f32_e32 v93, v30, v6
	v_mul_f32_e32 v46, v46, v6
	v_mul_f32_e32 v62, v62, v6
	v_mul_f32_e32 v78, v78, v6
	v_add_co_u32_e32 v6, vcc, s82, v2
	v_mul_f32_e32 v94, v31, v7
	v_mul_f32_e32 v47, v47, v7
	v_mul_f32_e32 v63, v63, v7
	v_mul_f32_e32 v79, v79, v7
	v_addc_co_u32_e32 v7, vcc, 0, v3, vcc
	s_mov_b32 s20, 0x9000
	s_waitcnt lgkmcnt(0)
	v_add_co_u32_e32 v8, vcc, s20, v2
	v_mul_f32_e32 v81, v16, v9
	v_mul_f32_e32 v95, v32, v9
	v_mul_f32_e32 v96, v33, v10
	v_mul_f32_e32 v48, v48, v9
	v_mul_f32_e32 v64, v64, v9
	v_addc_co_u32_e32 v9, vcc, 0, v3, vcc
	global_load_dwordx2 v[26:27], v[2:3], off
	global_load_dwordx2 v[28:29], v[4:5], off
	global_load_dwordx2 v[30:31], v[6:7], off
	global_load_dwordx2 v[32:33], v[8:9], off
	v_add_co_u32_e32 v4, vcc, s77, v2
	s_mov_b32 s21, 0xf000
	s_nop 0
	v_addc_co_u32_e32 v5, vcc, 0, v3, vcc
	v_add_co_u32_e32 v6, vcc, s21, v2
	s_mov_b32 s31, 0x15000
	s_nop 0
	v_addc_co_u32_e32 v7, vcc, 0, v3, vcc
	v_add_co_u32_e32 v8, vcc, s85, v2
	v_mul_f32_e32 v82, v17, v10
	s_nop 0
	v_addc_co_u32_e32 v9, vcc, 0, v3, vcc
	v_mul_f32_e32 v49, v49, v10
	v_mul_f32_e32 v65, v65, v10
	v_add_co_u32_e32 v10, vcc, s31, v2
	v_mul_f32_e32 v83, v18, v11
	v_mul_f32_e32 v84, v19, v12
	v_mul_f32_e32 v97, v34, v11
	v_mul_f32_e32 v98, v35, v12
	v_mul_f32_e32 v99, v36, v13
	v_mul_f32_e32 v100, v37, v14
	v_mul_f32_e32 v101, v38, v15
	v_mul_f32_e32 v50, v50, v11
	v_mul_f32_e32 v66, v66, v11
	v_addc_co_u32_e32 v11, vcc, 0, v3, vcc
	global_load_dwordx2 v[34:35], v[4:5], off
	global_load_dwordx2 v[36:37], v[6:7], off
	global_load_dwordx2 v[38:39], v[8:9], off
	global_load_dwordx2 v[18:19], v[10:11], off
	v_add_co_u32_e32 v4, vcc, s76, v2
	s_mov_b32 s33, 0x1b000
	s_nop 0
	v_addc_co_u32_e32 v5, vcc, 0, v3, vcc
	v_add_co_u32_e32 v6, vcc, s33, v2
	s_mov_b32 s4, 0x21000
	s_nop 0
	v_addc_co_u32_e32 v7, vcc, 0, v3, vcc
	v_add_co_u32_e32 v8, vcc, s92, v2
	v_mul_f32_e32 v85, v20, v13
	s_nop 0
	v_addc_co_u32_e32 v9, vcc, 0, v3, vcc
	v_add_co_u32_e32 v10, vcc, s4, v2
	v_mul_f32_e32 v86, v21, v14
	s_nop 0
	v_addc_co_u32_e32 v11, vcc, 0, v3, vcc
	v_mul_f32_e32 v22, v22, v15
	v_mul_f32_e32 v51, v51, v12
	v_mul_f32_e32 v52, v52, v13
	v_mul_f32_e32 v53, v53, v14
	v_mul_f32_e32 v54, v54, v15
	v_mul_f32_e32 v67, v67, v12
	v_mul_f32_e32 v68, v68, v13
	v_mul_f32_e32 v69, v69, v14
	v_mul_f32_e32 v70, v70, v15
	global_load_dwordx2 v[16:17], v[4:5], off
	global_load_dwordx2 v[14:15], v[6:7], off
	global_load_dwordx2 v[12:13], v[8:9], off
	s_nop 0
	global_load_dwordx2 v[10:11], v[10:11], off
	v_add_co_u32_e32 v4, vcc, s91, v2
	s_mov_b32 s35, 0x27000
	s_nop 0
	v_addc_co_u32_e32 v5, vcc, 0, v3, vcc
	v_add_co_u32_e32 v6, vcc, s35, v2
	s_mov_b32 s2, 0x2d000
	s_nop 0
	v_addc_co_u32_e32 v7, vcc, 0, v3, vcc
	v_add_co_u32_e32 v20, vcc, s94, v2
	s_nop 1
	v_addc_co_u32_e32 v21, vcc, 0, v3, vcc
	v_add_co_u32_e32 v2, vcc, s2, v2
	s_add_i32 s2, s73, 0
	s_nop 0
	v_addc_co_u32_e32 v3, vcc, 0, v3, vcc
	global_load_dwordx2 v[8:9], v[4:5], off
	s_nop 0
	global_load_dwordx2 v[6:7], v[6:7], off
	s_nop 0
	global_load_dwordx2 v[4:5], v[20:21], off
	s_nop 0
	global_load_dwordx2 v[2:3], v[2:3], off
	v_lshlrev_b32_e32 v20, 2, v181
	v_mul_u32_u24_e32 v21, 0x840, v176
	v_add3_u32 v20, s2, v20, v21
	s_waitcnt vmcnt(0)
	s_barrier
; #define LAS __attribute__((address_space(3)))
; __device__ __forceinline__ float bf2f(unsigned h) { return __uint_as_float(h << 16); }
; __device__ __forceinline__ unsigned cvt_pk_bf16(float lo, float hi) { unsigned r; asm volatile("v_cvt_pk_bf16_f32 %0, %1, %2" : "=v"(r) : "v"(lo), "v"(hi)); return r; }
; __device__ __forceinline__ int crow(int r, int hi) { return (r & 3) + 8 * (r >> 2) + 4 * hi; }
; template <bool SUBLN>
; __device__ __forceinline__ void attn_out(const AttnBufs& T, f32x16 (&o)[4], int type, int h, size_t orow0, LAS char* lds, int wid, int lane, int r32, int hi) {
;     ...
;     LAS float* stg = (LAS float*)(lds + wid * 16896);
; #pragma unroll
;     for (int d0 = 0; d0 < 4; ++d0)
; #pragma unroll
;         for (int r = 0; r < 16; ++r) stg[att::crow(r, hi) * 132 + d0 * 32 + r32] = o[d0][r];
;     asm volatile("s_waitcnt lgkmcnt(0)" ::: "memory");
;     f32x4 wsub = {1.f, 1.f, 1.f, 1.f};
;     if (SUBLN) { wsub = *(const f32x4*)(T.subln + c4) * (1.f - T.lam_init); }
; #pragma unroll
;     for (int i = 0; i < 16; ++i) {
;         f32x4 v = *(const LAS f32x4*)(stg + (2 * i + rr) * 132 + c4);
;         if (SUBLN) {
;             float s = (v[0] * v[0] + v[1] * v[1]) + (v[2] * v[2] + v[3] * v[3]);
;             s += __shfl_xor(s, 1); s += __shfl_xor(s, 2); s += __shfl_xor(s, 4); s += __shfl_xor(s, 8); s += __shfl_xor(s, 16);
;             v = v * (rsqrtf(s * (1.f / 128.f) + EPS)) * wsub;
;         }
;         u32x2 w; w.x = cvt_pk_bf16(v[0] * bf2f(gg[i].x & 0xffffu), v[1] * bf2f(gg[i].x >> 16)); w.y = cvt_pk_bf16(v[2] * bf2f(gg[i].y & 0xffffu), v[3] * bf2f(gg[i].y >> 16));
;         *(u32x2*)(op + (size_t)i * 2 * 3072) = w;
;     }
	ds_write2_b32 v20, v81, v95 offset1:32
	ds_write2_b32 v20, v82, v96 offset0:132 offset1:164
	v_add_u32_e32 v21, 0x400, v20
	v_add_u32_e32 v81, 0x1000, v20
	v_add_u32_e32 v82, 0x1400, v20
	ds_write2_b32 v21, v83, v97 offset0:8 offset1:40
	ds_write2_b32 v21, v84, v98 offset0:140 offset1:172
	ds_write2_b32 v81, v85, v99 offset0:32 offset1:64
	ds_write2_b32 v81, v86, v100 offset0:164 offset1:196
	ds_write2_b32 v82, v22, v101 offset0:40 offset1:72
	ds_write2_b32 v82, v23, v102 offset0:172 offset1:204
	v_add_u32_e32 v22, 0x2000, v20
	ds_write2_b32 v22, v87, v40 offset0:64 offset1:96
	ds_write2_b32 v22, v88, v41 offset0:196 offset1:228
	v_add_u32_e32 v23, 0x2400, v20
	v_add_u32_e32 v41, 0x3200, v20
	ds_write2_b32 v23, v89, v42 offset0:72 offset1:104
	ds_write2_b32 v23, v90, v43 offset0:204 offset1:236
	v_add_u32_e32 v40, 0x3000, v20
	ds_write2_b32 v41, v92, v45 offset0:100 offset1:132
	v_add_u32_e32 v41, 0x3400, v20
	v_add_u32_e32 v42, 0x3600, v20
	ds_write2_b32 v40, v91, v44 offset0:96 offset1:128
	ds_write2_b32 v41, v93, v46 offset0:104 offset1:136
	ds_write2_b32 v42, v94, v47 offset0:108 offset1:140
	ds_write2_b32 v20, v48, v64 offset0:64 offset1:96
	ds_write2_b32 v20, v49, v65 offset0:196 offset1:228
	ds_write2_b32 v21, v50, v66 offset0:72 offset1:104
	ds_write2_b32 v21, v51, v67 offset0:204 offset1:236
	ds_write2_b32 v81, v52, v68 offset0:96 offset1:128
	v_add_u32_e32 v21, 0x1200, v20
	ds_write2_b32 v21, v53, v69 offset0:100 offset1:132
	ds_write2_b32 v82, v54, v70 offset0:104 offset1:136
	v_add_u32_e32 v21, 0x1600, v20
	ds_write2_b32 v21, v55, v71 offset0:108 offset1:140
	ds_write2_b32 v22, v56, v72 offset0:128 offset1:160
	ds_write2_b32 v23, v57, v73 offset0:4 offset1:36
	ds_write2_b32 v23, v58, v74 offset0:136 offset1:168
	v_add_u32_e32 v21, 0x2800, v20
	v_add_u32_e32 v20, 0x3800, v20
	ds_write2_b32 v21, v59, v75 offset0:12 offset1:44
	ds_write2_b32 v40, v60, v76 offset0:160 offset1:192
	ds_write2_b32 v41, v61, v77 offset0:36 offset1:68
	ds_write2_b32 v41, v62, v78 offset0:168 offset1:200
	ds_write2_b32 v20, v63, v79 offset0:44 offset1:76
	v_lshlrev_b32_e32 v20, 2, v80
	v_mul_u32_u24_e32 v21, 0x210, v176
	s_waitcnt lgkmcnt(0)
	v_add3_u32 v42, s2, v20, v21
	ds_read_b128 v[56:59], v42
	v_readlane_b32 s2, v251, 48
	v_readlane_b32 s3, v251, 49
	s_nop 1
	v_mov_b64_e32 v[40:41], s[2:3]
	v_mad_u64_u32 v[40:41], s[2:3], v24, s5, v[40:41]
	v_lshlrev_b32_e32 v24, 16, v26
	ds_read_b128 v[60:63], v42 offset:1056
	s_waitcnt lgkmcnt(1)
	v_mul_f32_e32 v20, v56, v24
	v_and_b32_e32 v24, 0xffff0000, v26
	v_mul_f32_e32 v21, v57, v24
	v_cvt_pk_bf16_f32 v26, v20, v21
	v_lshlrev_b32_e32 v20, 16, v27
	v_and_b32_e32 v21, 0xffff0000, v27
	v_mul_f32_e32 v20, v58, v20
	v_mul_f32_e32 v21, v59, v21
	v_cvt_pk_bf16_f32 v27, v20, v21
	v_lshlrev_b32_e32 v24, 16, v28
	v_mad_i32_i24 v41, v25, s5, v41
	v_lshl_add_u64 v[0:1], v[40:41], 0, v[0:1]
	global_store_dwordx2 v[0:1], v[26:27], off
	ds_read_b128 v[56:59], v42 offset:2112
	s_waitcnt lgkmcnt(1)
	v_mul_f32_e32 v20, v60, v24
	v_and_b32_e32 v24, 0xffff0000, v28
	v_mul_f32_e32 v21, v61, v24
	v_cvt_pk_bf16_f32 v24, v20, v21
	v_lshlrev_b32_e32 v20, 16, v29
	v_and_b32_e32 v21, 0xffff0000, v29
	v_mul_f32_e32 v20, v62, v20
	v_mul_f32_e32 v21, v63, v21
	v_cvt_pk_bf16_f32 v25, v20, v21
	v_add_co_u32_e32 v26, vcc, s40, v0
	s_nop 1
	v_addc_co_u32_e32 v27, vcc, 0, v1, vcc
	global_store_dwordx2 v[26:27], v[24:25], off
	v_lshlrev_b32_e32 v24, 16, v30
	ds_read_b128 v[60:63], v42 offset:3168
	s_waitcnt lgkmcnt(1)
	v_mul_f32_e32 v20, v56, v24
	v_and_b32_e32 v24, 0xffff0000, v30
	v_mul_f32_e32 v21, v57, v24
	v_cvt_pk_bf16_f32 v24, v20, v21
	v_lshlrev_b32_e32 v20, 16, v31
	v_and_b32_e32 v21, 0xffff0000, v31
	v_mul_f32_e32 v20, v58, v20
	v_mul_f32_e32 v21, v59, v21
	v_cvt_pk_bf16_f32 v25, v20, v21
	v_add_co_u32_e32 v26, vcc, s82, v0
	s_nop 1
	v_addc_co_u32_e32 v27, vcc, 0, v1, vcc
	global_store_dwordx2 v[26:27], v[24:25], off
	v_lshlrev_b32_e32 v24, 16, v32
	ds_read_b128 v[56:59], v42 offset:4224
	s_waitcnt lgkmcnt(1)
	v_mul_f32_e32 v20, v60, v24
	v_and_b32_e32 v24, 0xffff0000, v32
	v_mul_f32_e32 v21, v61, v24
	v_cvt_pk_bf16_f32 v24, v20, v21
	v_lshlrev_b32_e32 v20, 16, v33
	v_and_b32_e32 v21, 0xffff0000, v33
	v_mul_f32_e32 v20, v62, v20
	v_mul_f32_e32 v21, v63, v21
	v_cvt_pk_bf16_f32 v25, v20, v21
	v_add_co_u32_e32 v26, vcc, s20, v0
	s_nop 1
	v_addc_co_u32_e32 v27, vcc, 0, v1, vcc
	global_store_dwordx2 v[26:27], v[24:25], off
	v_lshlrev_b32_e32 v24, 16, v34
	ds_read_b128 v[60:63], v42 offset:5280
	s_waitcnt lgkmcnt(1)
	v_mul_f32_e32 v20, v56, v24
	v_and_b32_e32 v24, 0xffff0000, v34
	v_mul_f32_e32 v21, v57, v24
	v_cvt_pk_bf16_f32 v24, v20, v21
	v_lshlrev_b32_e32 v20, 16, v35
	v_and_b32_e32 v21, 0xffff0000, v35
	v_mul_f32_e32 v20, v58, v20
	v_mul_f32_e32 v21, v59, v21
	v_cvt_pk_bf16_f32 v25, v20, v21
	v_add_co_u32_e32 v26, vcc, s77, v0
	s_nop 1
	v_addc_co_u32_e32 v27, vcc, 0, v1, vcc
	global_store_dwordx2 v[26:27], v[24:25], off
	v_lshlrev_b32_e32 v24, 16, v36
	ds_read_b128 v[56:59], v42 offset:6336
	s_waitcnt lgkmcnt(1)
; #define LAS __attribute__((address_space(3)))
; __device__ __forceinline__ float bf2f(unsigned h) { return __uint_as_float(h << 16); }
; __device__ __forceinline__ unsigned cvt_pk_bf16(float lo, float hi) { unsigned r; asm volatile("v_cvt_pk_bf16_f32 %0, %1, %2" : "=v"(r) : "v"(lo), "v"(hi)); return r; }
; template <bool SUBLN>
; __device__ __forceinline__ void attn_out(const AttnBufs& T, f32x16 (&o)[4], int type, int h, size_t orow0, LAS char* lds, int wid, int lane, int r32, int hi) {
;     ...
;     for (int i = 0; i < 16; ++i) {
;         f32x4 v = *(const LAS f32x4*)(stg + (2 * i + rr) * 132 + c4);
;         if (SUBLN) {
;             float s = (v[0] * v[0] + v[1] * v[1]) + (v[2] * v[2] + v[3] * v[3]);
;             s += __shfl_xor(s, 1); s += __shfl_xor(s, 2); s += __shfl_xor(s, 4); s += __shfl_xor(s, 8); s += __shfl_xor(s, 16);
;             v = v * (rsqrtf(s * (1.f / 128.f) + EPS)) * wsub;
;         }
;         u32x2 w; w.x = cvt_pk_bf16(v[0] * bf2f(gg[i].x & 0xffffu), v[1] * bf2f(gg[i].x >> 16)); w.y = cvt_pk_bf16(v[2] * bf2f(gg[i].y & 0xffffu), v[3] * bf2f(gg[i].y >> 16));
;         *(u32x2*)(op + (size_t)i * 2 * 3072) = w;
;     }
	v_mul_f32_e32 v20, v60, v24
	v_and_b32_e32 v24, 0xffff0000, v36
	v_mul_f32_e32 v21, v61, v24
	v_cvt_pk_bf16_f32 v24, v20, v21
	v_lshlrev_b32_e32 v20, 16, v37
	v_and_b32_e32 v21, 0xffff0000, v37
	v_mul_f32_e32 v20, v62, v20
	v_mul_f32_e32 v21, v63, v21
	v_cvt_pk_bf16_f32 v25, v20, v21
	v_add_co_u32_e32 v26, vcc, s21, v0
	s_nop 1
	v_addc_co_u32_e32 v27, vcc, 0, v1, vcc
	global_store_dwordx2 v[26:27], v[24:25], off
	v_lshlrev_b32_e32 v24, 16, v38
	ds_read_b128 v[60:63], v42 offset:7392
	s_waitcnt lgkmcnt(1)
	v_mul_f32_e32 v20, v56, v24
	v_and_b32_e32 v24, 0xffff0000, v38
	v_mul_f32_e32 v21, v57, v24
	v_cvt_pk_bf16_f32 v24, v20, v21
	v_lshlrev_b32_e32 v20, 16, v39
	v_and_b32_e32 v21, 0xffff0000, v39
	v_mul_f32_e32 v20, v58, v20
	v_mul_f32_e32 v21, v59, v21
	v_cvt_pk_bf16_f32 v25, v20, v21
	v_add_co_u32_e32 v26, vcc, s85, v0
	s_nop 1
	v_addc_co_u32_e32 v27, vcc, 0, v1, vcc
	global_store_dwordx2 v[26:27], v[24:25], off
	v_lshlrev_b32_e32 v24, 16, v18
	v_and_b32_e32 v18, 0xffff0000, v18
	ds_read_b128 v[56:59], v42 offset:8448
	s_waitcnt lgkmcnt(1)
	v_mul_f32_e32 v18, v61, v18
	v_mul_f32_e32 v20, v60, v24
	v_cvt_pk_bf16_f32 v24, v20, v18
	v_lshlrev_b32_e32 v18, 16, v19
	v_and_b32_e32 v19, 0xffff0000, v19
	v_mul_f32_e32 v18, v62, v18
	v_mul_f32_e32 v19, v63, v19
	v_cvt_pk_bf16_f32 v25, v18, v19
	v_add_co_u32_e32 v22, vcc, s31, v0
	s_nop 1
	v_addc_co_u32_e32 v23, vcc, 0, v1, vcc
	global_store_dwordx2 v[22:23], v[24:25], off
	v_lshlrev_b32_e32 v22, 16, v16
	v_and_b32_e32 v16, 0xffff0000, v16
	ds_read_b128 v[60:63], v42 offset:9504
	s_waitcnt lgkmcnt(1)
	v_mul_f32_e32 v16, v57, v16
	v_mul_f32_e32 v18, v56, v22
	v_cvt_pk_bf16_f32 v22, v18, v16
	v_lshlrev_b32_e32 v16, 16, v17
	v_and_b32_e32 v17, 0xffff0000, v17
	v_mul_f32_e32 v16, v58, v16
	v_mul_f32_e32 v17, v59, v17
	v_cvt_pk_bf16_f32 v23, v16, v17
	v_add_co_u32_e32 v20, vcc, s76, v0
	s_nop 1
	v_addc_co_u32_e32 v21, vcc, 0, v1, vcc
	global_store_dwordx2 v[20:21], v[22:23], off
	v_lshlrev_b32_e32 v20, 16, v14
	v_and_b32_e32 v14, 0xffff0000, v14
	ds_read_b128 v[56:59], v42 offset:10560
	s_waitcnt lgkmcnt(1)
	v_mul_f32_e32 v14, v61, v14
	v_mul_f32_e32 v16, v60, v20
	v_cvt_pk_bf16_f32 v20, v16, v14
	v_lshlrev_b32_e32 v14, 16, v15
	v_and_b32_e32 v15, 0xffff0000, v15
	v_mul_f32_e32 v14, v62, v14
	v_mul_f32_e32 v15, v63, v15
	v_cvt_pk_bf16_f32 v21, v14, v15
	v_add_co_u32_e32 v18, vcc, s33, v0
	s_nop 1
	v_addc_co_u32_e32 v19, vcc, 0, v1, vcc
	global_store_dwordx2 v[18:19], v[20:21], off
	v_lshlrev_b32_e32 v18, 16, v12
	v_and_b32_e32 v12, 0xffff0000, v12
	ds_read_b128 v[60:63], v42 offset:11616
	s_waitcnt lgkmcnt(1)
	v_mul_f32_e32 v12, v57, v12
	v_mul_f32_e32 v14, v56, v18
	v_cvt_pk_bf16_f32 v18, v14, v12
	v_lshlrev_b32_e32 v12, 16, v13
	v_and_b32_e32 v13, 0xffff0000, v13
	v_mul_f32_e32 v12, v58, v12
	v_mul_f32_e32 v13, v59, v13
	v_cvt_pk_bf16_f32 v19, v12, v13
	v_add_co_u32_e32 v16, vcc, s92, v0
	s_nop 1
	v_addc_co_u32_e32 v17, vcc, 0, v1, vcc
	global_store_dwordx2 v[16:17], v[18:19], off
	v_lshlrev_b32_e32 v16, 16, v10
	v_and_b32_e32 v10, 0xffff0000, v10
	ds_read_b128 v[56:59], v42 offset:12672
	s_waitcnt lgkmcnt(1)
	v_mul_f32_e32 v10, v61, v10
	v_mul_f32_e32 v12, v60, v16
	v_cvt_pk_bf16_f32 v16, v12, v10
	v_lshlrev_b32_e32 v10, 16, v11
	v_and_b32_e32 v11, 0xffff0000, v11
	v_mul_f32_e32 v10, v62, v10
	v_mul_f32_e32 v11, v63, v11
	v_cvt_pk_bf16_f32 v17, v10, v11
	v_add_co_u32_e32 v14, vcc, s4, v0
	s_nop 1
	v_addc_co_u32_e32 v15, vcc, 0, v1, vcc
	global_store_dwordx2 v[14:15], v[16:17], off
	v_lshlrev_b32_e32 v14, 16, v8
	v_and_b32_e32 v8, 0xffff0000, v8
	ds_read_b128 v[60:63], v42 offset:13728
	s_waitcnt lgkmcnt(1)
	v_mul_f32_e32 v8, v57, v8
	v_mul_f32_e32 v10, v56, v14
	v_cvt_pk_bf16_f32 v14, v10, v8
	v_lshlrev_b32_e32 v8, 16, v9
	v_and_b32_e32 v9, 0xffff0000, v9
	v_mul_f32_e32 v8, v58, v8
	v_mul_f32_e32 v9, v59, v9
	v_cvt_pk_bf16_f32 v15, v8, v9
	v_add_co_u32_e32 v12, vcc, s91, v0
	s_nop 1
	v_addc_co_u32_e32 v13, vcc, 0, v1, vcc
	global_store_dwordx2 v[12:13], v[14:15], off
	v_lshlrev_b32_e32 v12, 16, v6
	v_and_b32_e32 v6, 0xffff0000, v6
	ds_read_b128 v[56:59], v42 offset:14784
	s_waitcnt lgkmcnt(1)
	v_mul_f32_e32 v6, v61, v6
	v_mul_f32_e32 v8, v60, v12
	v_cvt_pk_bf16_f32 v12, v8, v6
	v_lshlrev_b32_e32 v6, 16, v7
	v_and_b32_e32 v7, 0xffff0000, v7
	v_mul_f32_e32 v6, v62, v6
	v_mul_f32_e32 v7, v63, v7
	v_cvt_pk_bf16_f32 v13, v6, v7
	v_add_co_u32_e32 v10, vcc, s35, v0
	s_nop 1
	v_addc_co_u32_e32 v11, vcc, 0, v1, vcc
	global_store_dwordx2 v[10:11], v[12:13], off
	v_lshlrev_b32_e32 v10, 16, v4
	v_and_b32_e32 v4, 0xffff0000, v4
	ds_read_b128 v[60:63], v42 offset:15840
	s_waitcnt lgkmcnt(1)
	v_mul_f32_e32 v4, v57, v4
	v_mul_f32_e32 v6, v56, v10
	v_cvt_pk_bf16_f32 v10, v6, v4
	v_lshlrev_b32_e32 v4, 16, v5
	v_and_b32_e32 v5, 0xffff0000, v5
	v_mul_f32_e32 v4, v58, v4
	v_mul_f32_e32 v5, v59, v5
	v_cvt_pk_bf16_f32 v11, v4, v5
	v_add_co_u32_e32 v8, vcc, s94, v0
	s_nop 1
	v_addc_co_u32_e32 v9, vcc, 0, v1, vcc
	global_store_dwordx2 v[8:9], v[10:11], off
	v_lshlrev_b32_e32 v8, 16, v2
	v_and_b32_e32 v2, 0xffff0000, v2
	s_waitcnt lgkmcnt(0)
	v_mul_f32_e32 v4, v60, v8
	v_mul_f32_e32 v2, v61, v2
	v_cvt_pk_bf16_f32 v2, v4, v2
	v_lshlrev_b32_e32 v4, 16, v3
	v_and_b32_e32 v3, 0xffff0000, v3
	v_mul_f32_e32 v3, v63, v3
	v_mul_f32_e32 v4, v62, v4
	v_cvt_pk_bf16_f32 v3, v4, v3
